# P2 chunk-inverse (wave 0 forward substitution): LDS row reads issued 15 deep ahead of the FMA chain instead of read-wait-use
# speedup vs baseline: 1.0347x; 1.0013x over previous
.LBB0_399:
	v_and_b32_e32 v25, 3, v155
	s_andn2_b64 vcc, exec, s[4:5]
	v_bfe_u32 v26, v155, 4, 1
	s_cbranch_vccnz .LBB0_405
	v_and_b32_e32 v12, 48, v155
	v_mul_u32_u24_e32 v0, 0x110, v12
	v_lshlrev_b32_e32 v1, 2, v12
	v_add3_u32 v13, s60, v0, v1
	ds_read_b128 v[142:145], v13 offset:272
	ds_read_b128 v[146:149], v13 offset:544
	ds_read_b128 v[150:153], v13 offset:816
	ds_read_b128 v[156:159], v13 offset:1088
	ds_read_b128 v[160:163], v13 offset:1360
	ds_read_b128 v[164:167], v13 offset:1376
	ds_read_b128 v[168:171], v13 offset:1632
	ds_read_b128 v[178:181], v13 offset:1648
	ds_read_b128 v[182:185], v13 offset:1904
	ds_read_b128 v[186:189], v13 offset:1920
	ds_read_b128 v[190:193], v13 offset:2176
	ds_read_b128 v[194:197], v13 offset:2192
	ds_read_b128 v[198:201], v13 offset:2448
	ds_read_b128 v[202:205], v13 offset:2464
	ds_read_b128 v[206:209], v13 offset:2480
	v_cmp_eq_u32_e32 vcc, 1, v177
	v_cndmask_b32_e64 v14, 0, 1.0, s[0:1]
	s_nop 0
	v_cndmask_b32_e64 v1, 0, 1.0, vcc
	v_cmp_eq_u32_e32 vcc, 2, v177
	s_waitcnt lgkmcnt(14)
	v_fma_f32 v15, -v14, v142, v1
	ds_read_b128 v[142:145], v13 offset:2720
	s_waitcnt lgkmcnt(14)
	v_fma_f32 v1, -v147, v15, 0
	v_cndmask_b32_e64 v0, 0, 1.0, vcc
	v_fma_f32 v0, -v14, v146, v0
	ds_read_b128 v[146:149], v13 offset:2736
	v_cmp_eq_u32_e32 vcc, 3, v177
	v_add_f32_e32 v17, v0, v1
	s_waitcnt lgkmcnt(14)
	v_fma_f32 v1, -v151, v15, 0
	v_cndmask_b32_e64 v0, 0, 1.0, vcc
	v_fma_f32 v0, -v14, v150, v0
	v_fma_f32 v0, -v152, v17, v0
	ds_read_b128 v[150:153], v13 offset:2752
	v_add_f32_e32 v19, v1, v0
	v_cmp_eq_u32_e32 vcc, 4, v177
	v_lshlrev_b32_e32 v32, 1, v177
	s_waitcnt lgkmcnt(14)
	v_fma_f32 v1, -v15, v157, 0
	v_cndmask_b32_e64 v8, 0, 1.0, vcc
	v_fma_f32 v0, -v14, v156, v8
	v_fma_f32 v0, -v158, v17, v0
	v_fma_f32 v1, -v19, v159, v1
	ds_read_b128 v[156:159], v13 offset:2992
	v_cmp_eq_u32_e32 vcc, 5, v177
	v_add_f32_e32 v20, v1, v0
	s_nop 0
	v_cndmask_b32_e64 v0, 0, 1.0, vcc
	s_waitcnt lgkmcnt(14)
	v_fma_f32 v4, -v14, v160, v0
	v_fma_f32 v1, -v15, v161, 0
	v_fma_f32 v6, -v162, v17, v4
	v_fma_f32 v1, -v19, v163, v1
	ds_read_b128 v[160:163], v13 offset:3008
	s_waitcnt lgkmcnt(14)
	v_fma_f32 v0, -v164, v20, v6
	ds_read_b128 v[164:167], v13 offset:3024
	v_cmp_eq_u32_e32 vcc, 6, v177
	v_add_f32_e32 v21, v1, v0
	s_waitcnt lgkmcnt(14)
	v_fma_f32 v1, -v15, v169, 0
	v_cndmask_b32_e64 v0, 0, 1.0, vcc
	v_fma_f32 v0, -v14, v168, v0
	v_fma_f32 v4, -v17, v170, v0
	v_fma_f32 v5, -v19, v171, v1
	ds_read_b128 v[168:171], v13 offset:3264
	s_waitcnt lgkmcnt(14)
	v_fma_f32 v4, -v178, v20, v4
	v_fma_f32 v5, -v179, v21, v5
	ds_read_b128 v[178:181], v13 offset:3280
	v_add_f32_e32 v22, v4, v5
	v_cmp_eq_u32_e32 vcc, 7, v177
	s_waitcnt lgkmcnt(14)
	v_fma_f32 v1, -v15, v183, 0
	v_fma_f32 v1, -v19, v185, v1
	v_cndmask_b32_e64 v8, 0, 1.0, vcc
	v_fma_f32 v0, -v14, v182, v8
	v_fma_f32 v0, -v17, v184, v0
	ds_read_b128 v[182:185], v13 offset:3296
	s_waitcnt lgkmcnt(14)
	v_fma_f32 v0, -v20, v186, v0
	v_fma_f32 v1, -v187, v21, v1
	v_fma_f32 v0, -v188, v22, v0
	ds_read_b128 v[186:189], v13 offset:3536
	v_add_f32_e32 v23, v1, v0
	v_cmp_eq_u32_e32 vcc, 8, v177
	s_waitcnt lgkmcnt(14)
	v_fma_f32 v1, -v15, v191, 0
	v_cndmask_b32_e64 v8, 0, 1.0, vcc
	v_fma_f32 v0, -v14, v190, v8
	v_fma_f32 v0, -v17, v192, v0
	v_fma_f32 v1, -v19, v193, v1
	ds_read_b128 v[190:193], v13 offset:3552
	s_waitcnt lgkmcnt(14)
	v_fma_f32 v0, -v20, v194, v0
	v_fma_f32 v1, -v21, v195, v1
	v_fma_f32 v4, -v196, v22, v0
	v_fma_f32 v5, -v23, v197, v1
	ds_read_b128 v[194:197], v13 offset:3568
	v_add_f32_e32 v27, v5, v4
	v_cmp_eq_u32_e32 vcc, 9, v177
	s_waitcnt lgkmcnt(14)
	v_fma_f32 v1, -v15, v199, 0
	v_cndmask_b32_e64 v8, 0, 1.0, vcc
	v_fma_f32 v0, -v14, v198, v8
	v_fma_f32 v0, -v17, v200, v0
	v_fma_f32 v8, -v19, v201, v1
	ds_read_b128 v[198:201], v13 offset:3584
	s_waitcnt lgkmcnt(14)
	v_fma_f32 v4, -v20, v202, v0
	v_fma_f32 v1, -v21, v203, v8
	v_fma_f32 v6, -v22, v204, v4
	v_fma_f32 v1, -v23, v205, v1
	ds_read_b128 v[202:205], v13 offset:3808
	s_waitcnt lgkmcnt(14)
	v_fma_f32 v0, -v206, v27, v6
	ds_read_b128 v[206:209], v13 offset:3824
	v_cmp_eq_u32_e32 vcc, 10, v177
	v_add_f32_e32 v28, v1, v0
	s_nop 0
	v_cndmask_b32_e64 v0, 0, 1.0, vcc
	s_waitcnt lgkmcnt(14)
	v_fma_f32 v0, -v14, v142, v0
	v_fma_f32 v1, -v15, v143, 0
	v_fma_f32 v4, -v17, v144, v0
	v_fma_f32 v5, -v19, v145, v1
	ds_read_b128 v[142:145], v13 offset:3840
	s_waitcnt lgkmcnt(14)
	v_fma_f32 v2, -v20, v146, v4
	v_fma_f32 v3, -v21, v147, v5
	v_fma_f32 v2, -v22, v148, v2
	v_fma_f32 v3, -v23, v149, v3
	ds_read_b128 v[146:149], v13 offset:3856
	s_waitcnt lgkmcnt(14)
	v_fma_f32 v4, -v27, v150, v2
	v_fma_f32 v5, -v151, v28, v3
	ds_read_b128 v[150:153], v13 offset:4080
	v_cmp_eq_u32_e32 vcc, 11, v177
	v_add_f32_e32 v29, v5, v4
	s_nop 0
	v_cndmask_b32_e64 v8, 0, 1.0, vcc
	s_waitcnt lgkmcnt(14)
	v_fma_f32 v0, -v14, v156, v8
	v_fma_f32 v1, -v15, v157, 0
	v_fma_f32 v8, -v17, v158, v0
	v_fma_f32 v9, -v19, v159, v1
	ds_read_b128 v[156:159], v13 offset:4096
	s_waitcnt lgkmcnt(14)
	v_fma_f32 v3, -v20, v160, v8
	v_fma_f32 v4, -v21, v161, v9
	v_fma_f32 v3, -v22, v162, v3
	v_fma_f32 v4, -v23, v163, v4
	ds_read_b128 v[160:163], v13 offset:4112
	s_waitcnt lgkmcnt(14)
	v_fma_f32 v0, -v27, v164, v3
	v_fma_f32 v1, -v28, v165, v4
	v_fma_f32 v0, -v166, v29, v0
	ds_read_b128 v[164:167], v13 offset:4128
	v_add_f32_e32 v30, v1, v0
	v_cmp_eq_u32_e32 vcc, 12, v177
	s_nop 1
	v_cndmask_b32_e64 v31, 0, 1.0, vcc
	v_cmp_eq_u32_e32 vcc, 13, v177
	s_waitcnt lgkmcnt(14)
	v_fma_f32 v0, -v14, v168, v31
	v_fma_f32 v1, -v15, v169, 0
	v_fma_f32 v0, -v17, v170, v0
	v_fma_f32 v1, -v19, v171, v1
	s_waitcnt lgkmcnt(13)
	v_fma_f32 v0, -v20, v178, v0
	v_fma_f32 v1, -v21, v179, v1
	v_fma_f32 v4, -v22, v180, v0
	v_fma_f32 v5, -v23, v181, v1
	s_waitcnt lgkmcnt(12)
	v_fma_f32 v4, -v27, v182, v4
	v_fma_f32 v5, -v28, v183, v5
	v_fma_f32 v4, -v29, v184, v4
	v_fma_f32 v5, -v30, v185, v5
	v_add_f32_e32 v8, v5, v4
	v_cndmask_b32_e64 v4, 0, 1.0, vcc
	s_waitcnt lgkmcnt(11)
	v_fma_f32 v0, -v14, v186, v4
	v_fma_f32 v1, -v15, v187, 0
	v_fma_f32 v9, -v17, v188, v0
	v_fma_f32 v10, -v19, v189, v1
	s_waitcnt lgkmcnt(10)
	v_fma_f32 v4, -v20, v190, v9
	v_fma_f32 v5, -v21, v191, v10
	v_fma_f32 v4, -v22, v192, v4
	v_fma_f32 v9, -v23, v193, v5
	s_waitcnt lgkmcnt(9)
	v_fma_f32 v0, -v27, v194, v4
	v_fma_f32 v1, -v28, v195, v9
	v_fma_f32 v5, -v29, v196, v0
	v_fma_f32 v6, -v30, v197, v1
	s_waitcnt lgkmcnt(8)
	v_fma_f32 v4, -v198, v8, v5
	v_cmp_eq_u32_e32 vcc, 14, v177
	v_add_f32_e32 v9, v6, v4
	s_waitcnt lgkmcnt(7)
	v_fma_f32 v1, -v15, v203, 0
	v_cndmask_b32_e64 v4, 0, 1.0, vcc
	v_fma_f32 v0, -v14, v202, v4
	v_fma_f32 v10, -v17, v204, v0
	v_fma_f32 v11, -v19, v205, v1
	v_cmp_eq_u32_e32 vcc, 15, v177
	s_waitcnt lgkmcnt(6)
	v_fma_f32 v4, -v20, v206, v10
	v_fma_f32 v5, -v21, v207, v11
	v_fma_f32 v4, -v22, v208, v4
	v_fma_f32 v10, -v23, v209, v5
	s_waitcnt lgkmcnt(5)
	v_fma_f32 v0, -v27, v142, v4
	v_fma_f32 v1, -v28, v143, v10
	v_fma_f32 v6, -v29, v144, v0
	v_fma_f32 v7, -v30, v145, v1
	s_waitcnt lgkmcnt(4)
	v_fma_f32 v4, -v8, v146, v6
	v_fma_f32 v5, -v147, v9, v7
	v_add_f32_e32 v10, v5, v4
	v_cndmask_b32_e64 v4, 0, 1.0, vcc
	s_waitcnt lgkmcnt(3)
	v_fma_f32 v0, -v14, v150, v4
	v_fma_f32 v1, -v15, v151, 0
	v_fma_f32 v11, -v17, v152, v0
	v_fma_f32 v31, -v19, v153, v1
	s_waitcnt lgkmcnt(2)
	v_fma_f32 v4, -v20, v156, v11
	v_fma_f32 v5, -v21, v157, v31
	v_fma_f32 v11, -v22, v158, v4
	v_fma_f32 v31, -v23, v159, v5
	s_waitcnt lgkmcnt(1)
	v_fma_f32 v0, -v27, v160, v11
	v_fma_f32 v1, -v28, v161, v31
	v_fma_f32 v0, -v29, v162, v0
	v_fma_f32 v1, -v30, v163, v1
	s_waitcnt lgkmcnt(0)
	v_fma_f32 v0, -v8, v164, v0
	v_fma_f32 v1, -v9, v165, v1
	v_fma_f32 v0, -v166, v10, v0
	v_add_f32_e32 v0, v1, v0
	v_lshlrev_b32_e32 v1, 1, v12
	v_add3_u32 v1, s59, v1, v32
	v_cvt_pk_bf16_f32 v2, v14, s0
	v_mad_u32_u24 v3, v12, s61, v1
	ds_write_b16 v3, v2
	v_cvt_pk_bf16_f32 v2, v15, s0
	ds_write_b16 v3, v2 offset:144
	v_cvt_pk_bf16_f32 v2, v17, s0
	ds_write_b16 v3, v2 offset:288
	v_cvt_pk_bf16_f32 v2, v19, s0
	ds_write_b16 v3, v2 offset:432
	v_cvt_pk_bf16_f32 v2, v20, s0
	ds_write_b16 v3, v2 offset:576
	v_cvt_pk_bf16_f32 v2, v21, s0
	ds_write_b16 v3, v2 offset:720
	v_cvt_pk_bf16_f32 v2, v22, s0
	ds_write_b16 v3, v2 offset:864
	v_cvt_pk_bf16_f32 v2, v23, s0
	ds_write_b16 v3, v2 offset:1008
	v_cvt_pk_bf16_f32 v2, v27, s0
	ds_write_b16 v3, v2 offset:1152
	v_cvt_pk_bf16_f32 v2, v28, s0
	ds_write_b16 v3, v2 offset:1296
	v_cvt_pk_bf16_f32 v2, v29, s0
	ds_write_b16 v3, v2 offset:1440
	v_cvt_pk_bf16_f32 v2, v30, s0
	ds_write_b16 v3, v2 offset:1584
	v_cvt_pk_bf16_f32 v2, v8, s0
	ds_write_b16 v3, v2 offset:1728
	v_cvt_pk_bf16_f32 v2, v9, s0
	ds_write_b16 v3, v2 offset:1872
	v_cvt_pk_bf16_f32 v2, v10, s0
	ds_write_b16 v3, v2 offset:2016
	v_or_b32_e32 v2, 15, v176
	v_cvt_pk_bf16_f32 v0, v0, s0
	v_mad_u32_u24 v1, v2, s61, v1
	ds_write_b16 v1, v0
	v_lshlrev_b32_e32 v0, 1, v176
	v_and_b32_e32 v21, 32, v0
	v_or_b32_e32 v20, 16, v21
	v_or_b32_e32 v22, v20, v177
	v_mov_b32_e32 v0, s60
	v_mad_u32_u24 v0, v22, s57, v0
	v_lshlrev_b32_e32 v1, 2, v21
	v_lshlrev_b32_e32 v2, 5, v18
	v_add3_u32 v4, v0, v1, v2
	ds_read_b128 v[0:3], v4
	ds_read_b128 v[4:7], v4 offset:16
	v_lshlrev_b32_e32 v27, 3, v18
	v_lshlrev_b32_e32 v19, 5, v26
	v_mov_b32_e32 v23, s59
	s_waitcnt lgkmcnt(1)
	v_cvt_pk_bf16_f32 v0, v0, v1
	v_cvt_pk_bf16_f32 v1, v2, v3
	s_waitcnt lgkmcnt(0)
	v_cvt_pk_bf16_f32 v2, v4, v5
	v_or3_b32 v4, v27, v19, v16
	v_mad_u32_u24 v4, v4, s61, v23
	v_lshlrev_b32_e32 v17, 3, v25
	v_lshlrev_b32_e32 v5, 6, v26
	v_cvt_pk_bf16_f32 v3, v6, v7
	v_add3_u32 v6, v4, v17, v5
	ds_read_b64_tr_b16 v[4:5], v6
	ds_read_b64_tr_b16 v[6:7], v6 offset:576
	s_waitcnt lgkmcnt(0)
	v_mfma_f32_32x32x16_bf16 v[0:15], v[0:3], v[4:7], 0
	v_cmp_gt_u32_e64 s[0:1], 16, v134
	v_lshlrev_b32_e32 v21, 1, v21
	v_cmp_lt_u32_e32 vcc, 15, v134
	v_add3_u32 v21, s59, v21, v32
	s_nop 7
	v_cndmask_b32_e64 v1, v9, v1, s[0:1]
	v_cndmask_b32_e64 v0, v8, v0, s[0:1]
	v_cvt_pk_bf16_f32 v0, v0, v1
	v_cndmask_b32_e64 v1, v11, v3, s[0:1]
	v_mad_u32_u24 v3, v22, s61, v23
	v_lshlrev_b32_e32 v8, 1, v20
	v_add3_u32 v3, v3, v27, v8
	ds_read2_b64 v[28:31], v3 offset1:2
	v_cndmask_b32_e64 v2, v10, v2, s[0:1]
	v_cvt_pk_bf16_f32 v1, v2, v1
	v_cndmask_b32_e64 v2, v13, v5, s[0:1]
	v_cndmask_b32_e64 v3, v12, v4, s[0:1]
	v_cvt_pk_bf16_f32 v2, v3, v2
	v_cndmask_b32_e64 v3, v15, v7, s[0:1]
	v_cndmask_b32_e64 v4, v14, v6, s[0:1]
	v_cvt_pk_bf16_f32 v3, v4, v3
	s_waitcnt lgkmcnt(0)
	s_nop 0
	v_mfma_f32_32x32x16_bf16 v[0:15], v[28:31], v[0:3], 0
	v_or_b32_e32 v28, 11, v135
	v_mul_u32_u24_e32 v29, 0x240, v18
	s_and_saveexec_b64 s[0:1], vcc
	s_xor_b64 s[0:1], exec, s[0:1]
	s_cbranch_execz .LBB0_402
	s_nop 6
	v_or_b32_e32 v1, v20, v135
	v_cvt_pk_bf16_f32 v0, -v8, s0
	v_mad_u32_u24 v1, v1, s61, v21
	ds_write_b16 v1, v0
	v_cvt_pk_bf16_f32 v0, -v9, s0
	ds_write_b16 v1, v0 offset:144
	v_cvt_pk_bf16_f32 v0, -v10, s0
	ds_write_b16 v1, v0 offset:288
	v_cvt_pk_bf16_f32 v0, -v11, s0
	ds_write_b16 v1, v0 offset:432
	v_cvt_pk_bf16_f32 v0, -v12, s0
	ds_write_b16 v1, v0 offset:1152
	v_cvt_pk_bf16_f32 v0, -v13, s0
	ds_write_b16 v1, v0 offset:1296
	v_cvt_pk_bf16_f32 v0, -v14, s0
	v_or_b32_e32 v28, 11, v135
	ds_write_b16 v1, v0 offset:1440
	v_or_b32_e32 v1, v28, v20
	v_cvt_pk_bf16_f32 v0, -v15, s0
	v_mad_u32_u24 v1, v1, s61, v21
	ds_write_b16 v1, v0
	v_mul_u32_u24_e32 v29, 0x240, v18
